# S5 pass1 (prep phase) inner loop rewritten with f32 u staging and packed-f32 math
# speedup vs baseline: 1.0366x; 1.0178x over previous
; DEV void lds_fence() { asm volatile("s_waitcnt lgkmcnt(0)" ::: "memory"); }
; DEV void s5_load_u(const h16* zrest, int rowbase, int g, char* ulds, int lane) {
; #pragma unroll
;   for (int i = 0; i < 8; ++i) {
;     int e = i * 64 + lane;
;     int r = e >> 1, hf = e & 1;
;     uint4 v = *(const uint4*)(zrest + (size_t)(rowbase + r) * ZR + g * 16 + hf * 8);
;     *(uint4*)(ulds + r * 32 + hf * 16) = v;
;   }
;   lds_fence();
; }
; DEV void s5_pass1_unit(const Params& p, const Ctx& cx, int l, int unit, char* wl, int lane) {
;   int c = unit % 65, bg = unit / 65, g = bg & 31, b = bg >> 5;
;   const h16* zrest = (const h16*)(p.ws + OFF_ZREST);
;   float2* F = (float2*)(p.ws + OFF_S5F);
;   s5_load_u(zrest, s5_rowbase(b, c), g, wl, lane);
;   float Br[16], Bi[16];
;   {
;     const float* pr = p.s5_b_re + ((size_t)(l * 32 + g) * 64 + lane) * 16;
;     const float* pi = p.s5_b_im + ((size_t)(l * 32 + g) * 64 + lane) * 16;
; #pragma unroll
;     for (int i = 0; i < 16; i += 4) {
;       float4 a = *(const float4*)(pr + i), bq = *(const float4*)(pi + i);
;       Br[i] = a.x; Br[i + 1] = a.y; Br[i + 2] = a.z; Br[i + 3] = a.w;
;       Bi[i] = bq.x; Bi[i + 1] = bq.y; Bi[i + 2] = bq.z; Bi[i + 3] = bq.w;
;     }
;   }
;   S5P pf = s5_params(p, cx, l, 0, g, lane), pb = s5_params(p, cx, l, 1, g, lane);
.LBB0_306:
	v_mov_b32_e32 v113, v112
	s_cmpk_gt_i32 s95, 0x81f
	s_mov_b64 s[0:1], -1
	s_waitcnt lgkmcnt(0)
	s_barrier
	s_cbranch_scc0 .LBB0_317
	s_lshl_b32 s0, s95, 3
	v_ashrrev_i32_e32 v0, 6, v113
	s_addk_i32 s0, 0xbf00
	v_add_u32_e32 v1, s0, v0
	s_mov_b32 s0, 0x7e07e07f
	v_mul_hi_i32 v2, v1, s0
	v_lshrrev_b32_e32 v3, 31, v2
	v_ashrrev_i32_e32 v2, 5, v2
	s_waitcnt vmcnt(0)
	v_add_u32_e32 v65, v2, v3
	v_lshl_add_u32 v2, v65, 6, v65
	s_waitcnt vmcnt(5)
	v_sub_u32_e32 v32, v1, v2
	v_ashrrev_i32_e32 v2, 5, v65
	v_cmp_ne_u32_e32 vcc, 0, v32
	s_and_saveexec_b64 s[0:1], vcc
	s_xor_b64 s[0:1], exec, s[0:1]
	v_lshlrev_b32_e32 v1, 14, v2
	v_lshlrev_b32_e32 v2, 8, v32
	s_movk_i32 s4, 0xff00
	v_add3_u32 v1, v2, v1, s4
	s_andn2_saveexec_b64 s[0:1], s[0:1]
	v_lshl_add_u32 v1, v2, 8, v168
	s_or_b64 exec, exec, s[0:1]
	s_waitcnt vmcnt(3)
	v_and_b32_e32 v34, 31, v65
	v_readlane_b32 s0, v241, 40
	v_lshlrev_b32_e32 v128, 5, v34
	v_readlane_b32 s1, v241, 41
	v_lshlrev_b32_e32 v4, 4, v113
	v_bfe_u32 v35, v113, 1, 5
	v_lshl_add_u64 v[2:3], s[0:1], 0, v[128:129]
	v_and_b32_e32 v128, 16, v4
	v_or_b32_e32 v36, 32, v35
	v_or_b32_e32 v42, 64, v35
	v_or_b32_e32 v43, 0x60, v35
	v_or_b32_e32 v44, 0x80, v35
	v_or_b32_e32 v45, 0xa0, v35
	v_or_b32_e32 v46, 0xc0, v35
	v_lshl_add_u64 v[26:27], v[2:3], 0, v[128:129]
	v_add_u32_e32 v2, v1, v35
	v_add_u32_e32 v4, v1, v36
	v_add_u32_e32 v10, v1, v42
	v_add_u32_e32 v12, v1, v43
	v_add_u32_e32 v18, v1, v44
	v_add_u32_e32 v20, v1, v45
	v_add_u32_e32 v28, v1, v46
	v_or_b32_e32 v47, 0xe0, v35
	v_mad_i64_i32 v[2:3], s[0:1], v2, s98, v[26:27]
	v_mad_i64_i32 v[6:7], s[0:1], v4, s98, v[26:27]
	v_mad_i64_i32 v[10:11], s[0:1], v10, s98, v[26:27]
	v_mad_i64_i32 v[14:15], s[0:1], v12, s98, v[26:27]
	v_mad_i64_i32 v[18:19], s[0:1], v18, s98, v[26:27]
	v_mad_i64_i32 v[22:23], s[0:1], v20, s98, v[26:27]
	v_mad_i64_i32 v[28:29], s[0:1], v28, s98, v[26:27]
	v_add_u32_e32 v1, v1, v47
	global_load_dwordx4 v[2:5], v[2:3], off
	s_nop 0
	global_load_dwordx4 v[6:9], v[6:7], off
	s_nop 0
	global_load_dwordx4 v[10:13], v[10:11], off
	s_nop 0
	global_load_dwordx4 v[14:17], v[14:15], off
	s_nop 0
	global_load_dwordx4 v[18:21], v[18:19], off
	s_nop 0
	global_load_dwordx4 v[22:25], v[22:23], off
	v_mad_i64_i32 v[30:31], s[0:1], v1, s98, v[26:27]
	global_load_dwordx4 v[26:29], v[28:29], off
	s_nop 0
	global_load_dwordx4 v[38:41], v[30:31], off
	v_lshl_add_u32 v33, v0, 14, 16
	v_add_u32_e32 v0, v33, v128
	v_add_u32_e32 v0, v0, v128
	v_lshl_add_u32 v1, v35, 6, v0
	v_or_b32_e32 v37, s89, v34
	v_lshl_add_u32 v30, v36, 6, v0
	v_lshl_add_u32 v31, v42, 6, v0
	v_lshl_add_u32 v35, v43, 6, v0
	v_lshl_add_u32 v36, v44, 6, v0
	v_lshl_add_u32 v42, v45, 6, v0
	v_lshl_add_u32 v43, v46, 6, v0
	v_lshl_add_u32 v0, v47, 6, v0
	v_readlane_b32 s68, v241, 56
	v_lshlrev_b32_e32 v128, 2, v37
	v_readlane_b32 s72, v241, 60
	v_readlane_b32 s73, v241, 61
	v_and_b32_e32 v66, 63, v113
	v_readlane_b32 s69, v241, 57
	v_readlane_b32 s70, v241, 58
	v_readlane_b32 s71, v241, 59
	v_readlane_b32 s74, v241, 62
	v_readlane_b32 s75, v241, 63
	v_readlane_b32 s76, v240, 0
	v_readlane_b32 s77, v240, 1
	s_mov_b32 s0, 0x3fb8aa3b
	v_readlane_b32 s78, v240, 2
	v_readlane_b32 s79, v240, 3
	v_readlane_b32 s80, v240, 4
	v_readlane_b32 s81, v240, 5
	v_readlane_b32 s82, v240, 6
	v_readlane_b32 s83, v240, 7
	s_waitcnt vmcnt(7)
	v_cvt_f32_f16_e32 v172, v2
	v_cvt_f32_f16_sdwa v173, v2 dst_sel:DWORD dst_unused:UNUSED_PAD src0_sel:WORD_1
	v_cvt_f32_f16_e32 v174, v3
	v_cvt_f32_f16_sdwa v175, v3 dst_sel:DWORD dst_unused:UNUSED_PAD src0_sel:WORD_1
	v_cvt_f32_f16_e32 v176, v4
	v_cvt_f32_f16_sdwa v177, v4 dst_sel:DWORD dst_unused:UNUSED_PAD src0_sel:WORD_1
	v_cvt_f32_f16_e32 v178, v5
	v_cvt_f32_f16_sdwa v179, v5 dst_sel:DWORD dst_unused:UNUSED_PAD src0_sel:WORD_1
	ds_write_b128 v1, v[172:175]
	ds_write_b128 v1, v[176:179] offset:16
	s_waitcnt vmcnt(6)
	v_cvt_f32_f16_e32 v180, v6
	v_cvt_f32_f16_sdwa v181, v6 dst_sel:DWORD dst_unused:UNUSED_PAD src0_sel:WORD_1
	v_cvt_f32_f16_e32 v182, v7
	v_cvt_f32_f16_sdwa v183, v7 dst_sel:DWORD dst_unused:UNUSED_PAD src0_sel:WORD_1
	v_cvt_f32_f16_e32 v184, v8
	v_cvt_f32_f16_sdwa v185, v8 dst_sel:DWORD dst_unused:UNUSED_PAD src0_sel:WORD_1
	v_cvt_f32_f16_e32 v186, v9
	v_cvt_f32_f16_sdwa v187, v9 dst_sel:DWORD dst_unused:UNUSED_PAD src0_sel:WORD_1
	ds_write_b128 v30, v[180:183]
	ds_write_b128 v30, v[184:187] offset:16
	s_waitcnt vmcnt(5)
	v_cvt_f32_f16_e32 v172, v10
	v_cvt_f32_f16_sdwa v173, v10 dst_sel:DWORD dst_unused:UNUSED_PAD src0_sel:WORD_1
	v_cvt_f32_f16_e32 v174, v11
	v_cvt_f32_f16_sdwa v175, v11 dst_sel:DWORD dst_unused:UNUSED_PAD src0_sel:WORD_1
	v_cvt_f32_f16_e32 v176, v12
	v_cvt_f32_f16_sdwa v177, v12 dst_sel:DWORD dst_unused:UNUSED_PAD src0_sel:WORD_1
	v_cvt_f32_f16_e32 v178, v13
	v_cvt_f32_f16_sdwa v179, v13 dst_sel:DWORD dst_unused:UNUSED_PAD src0_sel:WORD_1
	ds_write_b128 v31, v[172:175]
	ds_write_b128 v31, v[176:179] offset:16
	s_waitcnt vmcnt(4)
	v_cvt_f32_f16_e32 v180, v14
	v_cvt_f32_f16_sdwa v181, v14 dst_sel:DWORD dst_unused:UNUSED_PAD src0_sel:WORD_1
	v_cvt_f32_f16_e32 v182, v15
	v_cvt_f32_f16_sdwa v183, v15 dst_sel:DWORD dst_unused:UNUSED_PAD src0_sel:WORD_1
	v_cvt_f32_f16_e32 v184, v16
	v_cvt_f32_f16_sdwa v185, v16 dst_sel:DWORD dst_unused:UNUSED_PAD src0_sel:WORD_1
	v_cvt_f32_f16_e32 v186, v17
	v_cvt_f32_f16_sdwa v187, v17 dst_sel:DWORD dst_unused:UNUSED_PAD src0_sel:WORD_1
	ds_write_b128 v35, v[180:183]
	ds_write_b128 v35, v[184:187] offset:16
	s_waitcnt vmcnt(3)
; DEV S5P s5_params(const Params& p, const Ctx& cx, int l, int d, int g, int lane) {
;   int idx = ((l * 2 + d) * 32 + g) * 64 + lane;
;   float lr = fminf(p.s5_lam_re[idx], -1e-4f), li = p.s5_lam_im[idx];
;   float step = expf(p.s5_log_step[(l * 2 + d) * 32 + g]);
;   float xr = lr * step, xi = li * step;
;   float e = expf(xr), cs = cosf(xi), sn = sinf(xi);
;   S5P r;
;   r.ar = e * cs; r.ai = e * sn;
;   float sh = sinf(0.5f * xi);
;   float nr = expm1f(xr) * cs - 2.f * sh * sh, ni = e * sn;
; DEV void s5_load_u(const h16* zrest, int rowbase, int g, char* ulds, int lane) {
; #pragma unroll
;   for (int i = 0; i < 8; ++i) {
;     int e = i * 64 + lane;
;     int r = e >> 1, hf = e & 1;
;     uint4 v = *(const uint4*)(zrest + (size_t)(rowbase + r) * ZR + g * 16 + hf * 8);
;     *(uint4*)(ulds + r * 32 + hf * 16) = v;
;   }
	v_cvt_f32_f16_e32 v172, v18
	v_cvt_f32_f16_sdwa v173, v18 dst_sel:DWORD dst_unused:UNUSED_PAD src0_sel:WORD_1
	v_cvt_f32_f16_e32 v174, v19
	v_cvt_f32_f16_sdwa v175, v19 dst_sel:DWORD dst_unused:UNUSED_PAD src0_sel:WORD_1
	v_cvt_f32_f16_e32 v176, v20
	v_cvt_f32_f16_sdwa v177, v20 dst_sel:DWORD dst_unused:UNUSED_PAD src0_sel:WORD_1
	v_cvt_f32_f16_e32 v178, v21
	v_cvt_f32_f16_sdwa v179, v21 dst_sel:DWORD dst_unused:UNUSED_PAD src0_sel:WORD_1
	ds_write_b128 v36, v[172:175]
	ds_write_b128 v36, v[176:179] offset:16
	s_waitcnt vmcnt(2)
	v_cvt_f32_f16_e32 v180, v22
	v_cvt_f32_f16_sdwa v181, v22 dst_sel:DWORD dst_unused:UNUSED_PAD src0_sel:WORD_1
	v_cvt_f32_f16_e32 v182, v23
	v_cvt_f32_f16_sdwa v183, v23 dst_sel:DWORD dst_unused:UNUSED_PAD src0_sel:WORD_1
	v_cvt_f32_f16_e32 v184, v24
	v_cvt_f32_f16_sdwa v185, v24 dst_sel:DWORD dst_unused:UNUSED_PAD src0_sel:WORD_1
	v_cvt_f32_f16_e32 v186, v25
	v_cvt_f32_f16_sdwa v187, v25 dst_sel:DWORD dst_unused:UNUSED_PAD src0_sel:WORD_1
	ds_write_b128 v42, v[180:183]
	ds_write_b128 v42, v[184:187] offset:16
	s_waitcnt vmcnt(1)
	v_cvt_f32_f16_e32 v172, v26
	v_cvt_f32_f16_sdwa v173, v26 dst_sel:DWORD dst_unused:UNUSED_PAD src0_sel:WORD_1
	v_cvt_f32_f16_e32 v174, v27
	v_cvt_f32_f16_sdwa v175, v27 dst_sel:DWORD dst_unused:UNUSED_PAD src0_sel:WORD_1
	v_cvt_f32_f16_e32 v176, v28
	v_cvt_f32_f16_sdwa v177, v28 dst_sel:DWORD dst_unused:UNUSED_PAD src0_sel:WORD_1
	v_cvt_f32_f16_e32 v178, v29
	v_cvt_f32_f16_sdwa v179, v29 dst_sel:DWORD dst_unused:UNUSED_PAD src0_sel:WORD_1
	ds_write_b128 v43, v[172:175]
	ds_write_b128 v43, v[176:179] offset:16
	s_waitcnt vmcnt(0)
	v_cvt_f32_f16_e32 v180, v38
	v_cvt_f32_f16_sdwa v181, v38 dst_sel:DWORD dst_unused:UNUSED_PAD src0_sel:WORD_1
	v_cvt_f32_f16_e32 v182, v39
	v_cvt_f32_f16_sdwa v183, v39 dst_sel:DWORD dst_unused:UNUSED_PAD src0_sel:WORD_1
	v_cvt_f32_f16_e32 v184, v40
	v_cvt_f32_f16_sdwa v185, v40 dst_sel:DWORD dst_unused:UNUSED_PAD src0_sel:WORD_1
	v_cvt_f32_f16_e32 v186, v41
	v_cvt_f32_f16_sdwa v187, v41 dst_sel:DWORD dst_unused:UNUSED_PAD src0_sel:WORD_1
	ds_write_b128 v0, v[180:183]
	ds_write_b128 v0, v[184:187] offset:16
	s_waitcnt lgkmcnt(0)
	global_load_dword v36, v128, s[72:73]
	v_or_b32_e32 v0, s88, v34
	v_lshlrev_b32_e32 v42, 2, v66
	v_lshlrev_b32_e32 v0, 12, v0
	v_lshl_or_b32 v1, v37, 8, v42
	v_lshl_or_b32 v16, v66, 6, v0
	global_load_dword v34, v1, s[68:69]
	global_load_dword v35, v1, s[70:71]
	s_nop 0
	global_load_dwordx4 v[0:3], v16, s[74:75] offset:48
	global_load_dwordx4 v[28:31], v16, s[76:77] offset:48
	global_load_dwordx4 v[4:7], v16, s[74:75] offset:32
	global_load_dwordx4 v[24:27], v16, s[76:77] offset:32
	global_load_dwordx4 v[8:11], v16, s[74:75] offset:16
	global_load_dwordx4 v[20:23], v16, s[76:77] offset:16
	global_load_dwordx4 v[12:15], v16, s[74:75]
	s_nop 0
	global_load_dwordx4 v[16:19], v16, s[76:77]
	s_waitcnt vmcnt(10)
	v_mul_f32_e32 v38, 0x3fb8aa3b, v36
	v_fma_f32 v39, v36, s0, -v38
	v_rndne_f32_e32 v40, v38
	v_fmac_f32_e32 v39, 0x32a5705f, v36
	v_sub_f32_e32 v38, v38, v40
	v_add_f32_e32 v38, v38, v39
	v_cvt_i32_f32_e32 v40, v40
	v_exp_f32_e32 v38, v38
	s_mov_b32 s0, 0xc2ce8ed0
	v_cmp_ngt_f32_e32 vcc, s0, v36
	s_mov_b32 s0, 0x42b17218
	v_ldexp_f32 v38, v38, v40
	v_cndmask_b32_e32 v38, 0, v38, vcc
	v_cmp_nlt_f32_e32 vcc, s0, v36
	s_brev_b32 s0, 18
	s_nop 0
	v_cndmask_b32_e32 v40, v163, v38, vcc
	s_waitcnt vmcnt(8)
	v_mul_f32_e32 v36, v35, v40
	v_and_b32_e32 v39, 0x7fffffff, v36
	v_lshrrev_b32_e32 v38, 23, v39
	v_and_b32_e32 v41, 0x7fffff, v39
	v_cmp_nlt_f32_e64 s[84:85], |v36|, s0
	v_add_u32_e32 v46, 0xffffff88, v38
	v_or_b32_e32 v44, 0x800000, v41
	s_and_saveexec_b64 s[0:1], s[84:85]
	s_xor_b64 s[86:87], exec, s[0:1]
	s_cbranch_execz .LBB0_313
	s_mov_b32 s4, 0xfe5163ab
	v_mad_u64_u32 v[48:49], s[4:5], v44, s4, 0
	v_mov_b32_e32 v50, v49
	v_mov_b32_e32 v51, v129
	s_mov_b32 s4, 0x3c439041
	v_mad_u64_u32 v[50:51], s[4:5], v44, s4, v[50:51]
	v_mov_b32_e32 v52, v51
	v_mov_b32_e32 v53, v129
	s_mov_b32 s4, 0xdb629599
	v_mad_u64_u32 v[52:53], s[4:5], v44, s4, v[52:53]
	v_cmp_lt_u32_e32 vcc, 63, v46
	v_mov_b32_e32 v54, v53
	v_mov_b32_e32 v55, v129
	s_mov_b32 s4, 0xf534ddc0
	v_cndmask_b32_e32 v38, 0, v164, vcc
	v_mad_u64_u32 v[54:55], s[4:5], v44, s4, v[54:55]
	v_add_u32_e32 v38, v38, v46
	v_mov_b32_e32 v56, v55
	v_mov_b32_e32 v57, v129
	s_mov_b32 s4, 0xfc2757d1
	v_cmp_lt_u32_e64 s[0:1], 31, v38
	v_mad_u64_u32 v[56:57], s[4:5], v44, s4, v[56:57]
	s_nop 0
	v_cndmask_b32_e64 v41, 0, v165, s[0:1]
	v_mov_b32_e32 v58, v57
	v_mov_b32_e32 v59, v129
	s_mov_b32 s4, 0x4e441529
	v_add_u32_e32 v38, v41, v38
	v_mad_u64_u32 v[58:59], s[4:5], v44, s4, v[58:59]
	v_cmp_lt_u32_e64 s[38:39], 31, v38
	v_mov_b32_e32 v60, v59
	v_mov_b32_e32 v61, v129
	s_mov_b32 s4, 0xa2f9836e
	v_cndmask_b32_e64 v41, 0, v165, s[38:39]
	v_mad_u64_u32 v[60:61], s[4:5], v44, s4, v[60:61]
	v_add_u32_e32 v38, v41, v38
	v_cndmask_b32_e32 v41, v58, v54, vcc
	v_cndmask_b32_e32 v43, v60, v56, vcc
	v_cndmask_b32_e32 v47, v61, v58, vcc
	v_cndmask_b32_e64 v45, v43, v41, s[0:1]
	v_cndmask_b32_e64 v43, v47, v43, s[0:1]
	v_cndmask_b32_e32 v47, v56, v52, vcc
	v_cndmask_b32_e64 v41, v41, v47, s[0:1]
	v_sub_u32_e32 v49, 32, v38
	v_cmp_eq_u32_e64 s[40:41], 0, v38
	v_cndmask_b32_e32 v38, v54, v50, vcc
	v_cndmask_b32_e64 v43, v43, v45, s[38:39]
	v_cndmask_b32_e64 v45, v45, v41, s[38:39]
	v_cndmask_b32_e64 v47, v47, v38, s[0:1]
	v_alignbit_b32 v51, v43, v45, v49
	v_cndmask_b32_e64 v41, v41, v47, s[38:39]
	v_cndmask_b32_e64 v43, v51, v43, s[40:41]
	v_alignbit_b32 v50, v45, v41, v49
	v_cndmask_b32_e32 v48, v52, v48, vcc
	v_cndmask_b32_e64 v45, v50, v45, s[40:41]
	v_bfe_u32 v53, v43, 29, 1
	v_cndmask_b32_e64 v38, v38, v48, s[0:1]
	v_alignbit_b32 v50, v43, v45, 30
	v_sub_u32_e32 v54, 0, v53
	v_cndmask_b32_e64 v38, v47, v38, s[38:39]
	v_xor_b32_e32 v50, v50, v54
	v_alignbit_b32 v47, v41, v38, v49
	v_cndmask_b32_e64 v41, v47, v41, s[40:41]
	v_ffbh_u32_e32 v47, v50
	v_alignbit_b32 v45, v45, v41, 30
	v_min_u32_e32 v47, 32, v47
	v_alignbit_b32 v38, v41, v38, 30
	v_xor_b32_e32 v45, v45, v54
	v_sub_u32_e32 v48, 31, v47
	v_xor_b32_e32 v38, v38, v54
	v_alignbit_b32 v49, v50, v45, v48
	v_alignbit_b32 v38, v45, v38, v48
	v_alignbit_b32 v41, v49, v38, 9
	v_ffbh_u32_e32 v45, v41
	v_min_u32_e32 v45, 32, v45
	v_lshrrev_b32_e32 v51, 29, v43
	v_not_b32_e32 v48, v45
	v_alignbit_b32 v38, v41, v38, v48
	v_lshlrev_b32_e32 v41, 31, v51
	v_or_b32_e32 v48, 0x33000000, v41
	v_add_lshl_u32 v45, v45, v47, 23
	v_lshrrev_b32_e32 v38, 9, v38
	v_sub_u32_e32 v45, v48, v45
	v_or_b32_e32 v41, 0.5, v41
	v_lshlrev_b32_e32 v47, 23, v47
	v_or_b32_e32 v38, v45, v38
	v_lshrrev_b32_e32 v45, 9, v49
	v_sub_u32_e32 v41, v41, v47
	v_or_b32_e32 v41, v45, v41
	v_mul_f32_e32 v45, 0x3fc90fda, v41
	s_mov_b32 s0, 0x3fc90fda
	v_fma_f32 v47, v41, s0, -v45
	v_fmac_f32_e32 v47, 0x33a22168, v41
	v_fmac_f32_e32 v47, 0x3fc90fda, v38
	v_lshrrev_b32_e32 v41, 30, v43
	v_add_f32_e32 v38, v45, v47
	v_add_u32_e32 v43, v53, v41

; DEV S5P s5_params(const Params& p, const Ctx& cx, int l, int d, int g, int lane) {
;   int idx = ((l * 2 + d) * 32 + g) * 64 + lane;
;   float lr = fminf(p.s5_lam_re[idx], -1e-4f), li = p.s5_lam_im[idx];
;   float step = expf(p.s5_log_step[(l * 2 + d) * 32 + g]);
;   float xr = lr * step, xi = li * step;
;   float e = expf(xr), cs = cosf(xi), sn = sinf(xi);
;   S5P r;
;   r.ar = e * cs; r.ai = e * sn;
;   float sh = sinf(0.5f * xi);
;   float nr = expm1f(xr) * cs - 2.f * sh * sh, ni = e * sn;
;   float inv = 1.f / (lr * lr + li * li);
;   r.br = (nr * lr + ni * li) * inv;
;   r.bi = (ni * lr - nr * li) * inv;
;   return r;
; }
; DEV void s5_pass1_unit(const Params& p, const Ctx& cx, int l, int unit, char* wl, int lane) {
;     ...
;   S5P pf = s5_params(p, cx, l, 0, g, lane), pb = s5_params(p, cx, l, 1, g, lane);
;   float xr = 0, xi = 0, yr = 0, yi = 0, pwr = 1.f, pwi = 0.f;
.LBB0_336:
	s_or_b64 exec, exec, s[0:1]
	v_max_f32_e32 v34, v34, v34
	v_min_f32_e32 v34, 0xb8d1b717, v34
	v_mul_f32_e32 v73, v34, v40
	v_mul_f32_e32 v40, 0x3fb8aa3b, v73
	s_mov_b32 s4, 0x3fb8aa3b
	v_fma_f32 v42, v73, s4, -v40
	v_rndne_f32_e32 v75, v40
	v_fmac_f32_e32 v42, 0x32a5705f, v73
	v_sub_f32_e32 v40, v40, v75
	v_add_f32_e32 v40, v40, v42
	v_exp_f32_e32 v40, v40
	v_cvt_i32_f32_e32 v77, v75
	s_mov_b32 s5, 0xc2ce8ed0
	v_cmp_ngt_f32_e32 vcc, s5, v73
	s_mov_b32 s9, 0x42b17218
	v_ldexp_f32 v40, v40, v77
	v_cndmask_b32_e32 v40, 0, v40, vcc
	v_cmp_nlt_f32_e32 vcc, s9, v73
	s_movk_i32 s10, 0x1f8
	v_mov_b32_e32 v56, v38
	v_cndmask_b32_e32 v54, v163, v40, vcc
	v_cmp_class_f32_e64 vcc, v36, s10
	v_xor_b32_e32 v36, v39, v36
	v_lshlrev_b32_e32 v39, 30, v45
	v_and_b32_e32 v39, 0x80000000, v39
	v_xor_b32_e32 v36, v36, v39
	v_mul_f32_e32 v39, v41, v41
	v_fmamk_f32 v48, v39, 0xb94c1982, v156
	v_fmaak_f32 v57, v39, v48, 0xbe2aaa9d
	v_fmamk_f32 v48, v39, 0x37d75334, v157
	v_fmaak_f32 v48, v39, v48, 0x3d2aabf7
	v_fmaak_f32 v55, v39, v48, 0xbf000004
	v_pk_mul_f32 v[56:57], v[38:39], v[56:57]
	v_fma_f32 v55, v39, v55, 1.0
	v_fmamk_f32 v39, v56, 0x37d75334, v157
	v_and_b32_e32 v40, 1, v45
	v_fmaak_f32 v39, v56, v39, 0x3d2aabf7
	v_cmp_eq_u32_e64 s[38:39], 0, v40
	v_fmaak_f32 v40, v56, v39, 0xbf000004
	v_fmamk_f32 v39, v56, 0xb94c1982, v156
	v_mov_b32_e32 v131, v41
	v_fmaak_f32 v39, v56, v39, 0xbe2aaa9d
	v_and_b32_e32 v45, 1, v43
	v_pk_fma_f32 v[40:41], v[56:57], v[40:41], v[130:131]
	v_mul_f32_e32 v39, v56, v39
	v_lshlrev_b32_e32 v43, 30, v43
	v_cmp_eq_u32_e64 s[0:1], 0, v45
	v_fmac_f32_e32 v38, v38, v39
	v_cndmask_b32_e64 v39, v55, v41, s[38:39]
	v_and_b32_e32 v43, 0x80000000, v43
	v_cndmask_b32_e64 v38, -v38, v40, s[0:1]
	v_xor_b32_e32 v36, v36, v39
	v_xor_b32_e32 v38, v43, v38
	v_cndmask_b32_e32 v41, v166, v36, vcc
	s_waitcnt vmcnt(0)
	v_max_f32_e32 v36, v50, v50
	v_cndmask_b32_e32 v40, v166, v38, vcc
	v_min_f32_e32 v36, 0xb8d1b717, v36
	v_pk_mul_f32 v[38:39], v[54:55], v[40:41] op_sel_hi:[0,1]
	v_mul_f32_e32 v41, v36, v51
	v_mul_f32_e32 v43, 0x3fb8aa3b, v41
	v_fma_f32 v45, v41, s4, -v43
	v_rndne_f32_e32 v78, v43
	v_fmac_f32_e32 v45, 0x32a5705f, v41
	v_sub_f32_e32 v43, v43, v78
	v_add_f32_e32 v43, v43, v45
	v_exp_f32_e32 v43, v43
	v_cvt_i32_f32_e32 v79, v78
	v_cmp_ngt_f32_e32 vcc, s5, v41
	v_lshlrev_b32_e32 v45, 30, v53
	v_and_b32_e32 v45, 0x80000000, v45
	v_ldexp_f32 v43, v43, v79
	v_cndmask_b32_e32 v43, 0, v43, vcc
	v_cmp_nlt_f32_e32 vcc, s9, v41
	v_mov_b32_e32 v131, v47
	v_mov_b32_e32 v42, 0
	v_cndmask_b32_e32 v50, v163, v43, vcc
	v_xor_b32_e32 v43, v49, v46
	v_xor_b32_e32 v43, v43, v45
	v_mul_f32_e32 v45, v47, v47
	v_fmamk_f32 v51, v45, 0xb94c1982, v156
	v_cmp_class_f32_e64 vcc, v46, s10
	v_and_b32_e32 v46, 1, v53
	v_and_b32_e32 v49, 1, v52
	v_fmaak_f32 v53, v45, v51, 0xbe2aaa9d
	v_fmamk_f32 v51, v45, 0x37d75334, v157
	v_lshlrev_b32_e32 v52, 30, v52
	v_fmaak_f32 v51, v45, v51, 0x3d2aabf7
	v_and_b32_e32 v54, 0x80000000, v52
	v_mov_b32_e32 v52, v44
	v_fmaak_f32 v51, v45, v51, 0xbf000004
	v_pk_mul_f32 v[52:53], v[44:45], v[52:53]
	v_fma_f32 v51, v45, v51, 1.0
	v_fmamk_f32 v45, v52, 0x37d75334, v157
	v_fmaak_f32 v45, v52, v45, 0x3d2aabf7
	v_cmp_eq_u32_e64 s[38:39], 0, v46
	v_fmaak_f32 v46, v52, v45, 0xbf000004
	v_fmamk_f32 v45, v52, 0xb94c1982, v156
	v_fmaak_f32 v45, v52, v45, 0xbe2aaa9d
	v_mul_f32_e32 v45, v52, v45
	v_cmp_eq_u32_e64 s[0:1], 0, v49
	v_pk_fma_f32 v[46:47], v[46:47], v[52:53], v[130:131]
	v_fmac_f32_e32 v44, v44, v45
	v_cndmask_b32_e64 v45, v51, v47, s[38:39]
	v_cndmask_b32_e64 v44, -v44, v46, s[0:1]
	v_xor_b32_e32 v43, v43, v45
	v_xor_b32_e32 v44, v54, v44
	v_cndmask_b32_e32 v45, v166, v43, vcc
	v_cndmask_b32_e32 v44, v166, v44, vcc
	v_pk_mul_f32 v[46:47], v[50:51], v[44:45] op_sel_hi:[0,1]
	v_mov_b32_e32 v48, 1.0
	s_mov_b32 s8, 0
	v_mov_b32_e32 v50, v3
	v_mov_b32_e32 v51, v31
	v_mov_b32_e32 v3, v30
	v_mov_b32_e32 v30, v1
	v_mov_b32_e32 v31, v29
	v_mov_b32_e32 v1, v28
	v_mov_b32_e32 v28, v7
	v_mov_b32_e32 v29, v27
	v_mov_b32_e32 v7, v26
	v_mov_b32_e32 v26, v5
	v_mov_b32_e32 v27, v25
	v_mov_b32_e32 v5, v24
	v_mov_b32_e32 v24, v11
	v_mov_b32_e32 v25, v23
	v_mov_b32_e32 v11, v22
	v_mov_b32_e32 v52, v9
	v_mov_b32_e32 v53, v21
	v_mov_b32_e32 v9, v20
	v_mov_b32_e32 v54, v15
	v_mov_b32_e32 v55, v19
	v_mov_b32_e32 v15, v18
	v_mov_b32_e32 v56, v13
	v_mov_b32_e32 v57, v17
	v_mov_b32_e32 v13, v16
	v_pk_mov_b32 v[58:59], v[38:39], v[38:39] op_sel:[1,0]
	v_pk_mov_b32 v[60:61], v[46:47], v[46:47] op_sel:[1,0]
	v_mov_b32_e32 v64, 0
	v_mov_b32_e32 v62, 0
	v_mov_b32_e32 v63, v42
	v_mov_b32_e32 v49, v42
	v_add_u32_e32 v45, s8, v33
	ds_read_b128 v[204:207], v45 offset:0
	ds_read_b128 v[208:211], v45 offset:16
	ds_read_b128 v[212:215], v45 offset:32
	ds_read_b128 v[216:219], v45 offset:48
; DEV void s5_pass1_unit(const Params& p, const Ctx& cx, int l, int unit, char* wl, int lane) {
;     ...
;   for (int t = 0; t < 256; ++t) {
;     h16x8 u0 = *(const h16x8*)(wl + t * 32), u1 = *(const h16x8*)(wl + t * 32 + 16);
;     float br = 0, bi = 0;
; #pragma unroll
;     for (int i = 0; i < 8; ++i) { float u = (float)u0[i]; br = fmaf(u, Br[i], br); bi = fmaf(u, Bi[i], bi); }
; #pragma unroll
;     for (int i = 0; i < 8; ++i) { float u = (float)u1[i]; br = fmaf(u, Br[8 + i], br); bi = fmaf(u, Bi[8 + i], bi); }
;     float nxr = pf.ar * xr - pf.ai * xi + br, nxi = pf.ar * xi + pf.ai * xr + bi;
;     xr = nxr; xi = nxi;
;     yr += pwr * br - pwi * bi; yi += pwr * bi + pwi * br;
;     float npr = pwr * pb.ar - pwi * pb.ai, npi = pwr * pb.ai + pwi * pb.ar;
;     pwr = npr; pwi = npi;
;   }
.Ls5p1_loop:
	ds_read_b128 v[220:223], v45 offset:64
	ds_read_b128 v[224:227], v45 offset:80
	ds_read_b128 v[228:231], v45 offset:96
	ds_read_b128 v[232:235], v45 offset:112
	s_waitcnt lgkmcnt(4)
	v_pk_mul_f32 v[236:237], v[204:205], v[12:13] op_sel:[0,0] op_sel_hi:[0,1]
	v_pk_fma_f32 v[236:237], v[204:205], v[56:57], v[236:237] op_sel:[1,0,0] op_sel_hi:[1,1,1]
	v_pk_fma_f32 v[236:237], v[206:207], v[14:15], v[236:237] op_sel:[0,0,0] op_sel_hi:[0,1,1]
	v_pk_fma_f32 v[236:237], v[206:207], v[54:55], v[236:237] op_sel:[1,0,0] op_sel_hi:[1,1,1]
	v_pk_fma_f32 v[236:237], v[208:209], v[8:9], v[236:237] op_sel:[0,0,0] op_sel_hi:[0,1,1]
	v_pk_fma_f32 v[236:237], v[208:209], v[52:53], v[236:237] op_sel:[1,0,0] op_sel_hi:[1,1,1]
	v_pk_fma_f32 v[236:237], v[210:211], v[10:11], v[236:237] op_sel:[0,0,0] op_sel_hi:[0,1,1]
	v_pk_fma_f32 v[236:237], v[210:211], v[24:25], v[236:237] op_sel:[1,0,0] op_sel_hi:[1,1,1]
	v_pk_fma_f32 v[236:237], v[212:213], v[4:5], v[236:237] op_sel:[0,0,0] op_sel_hi:[0,1,1]
	v_pk_fma_f32 v[236:237], v[212:213], v[26:27], v[236:237] op_sel:[1,0,0] op_sel_hi:[1,1,1]
	v_pk_fma_f32 v[236:237], v[214:215], v[6:7], v[236:237] op_sel:[0,0,0] op_sel_hi:[0,1,1]
	v_pk_fma_f32 v[236:237], v[214:215], v[28:29], v[236:237] op_sel:[1,0,0] op_sel_hi:[1,1,1]
	v_pk_fma_f32 v[236:237], v[216:217], v[0:1], v[236:237] op_sel:[0,0,0] op_sel_hi:[0,1,1]
	v_pk_fma_f32 v[236:237], v[216:217], v[30:31], v[236:237] op_sel:[1,0,0] op_sel_hi:[1,1,1]
	v_pk_fma_f32 v[236:237], v[218:219], v[2:3], v[236:237] op_sel:[0,0,0] op_sel_hi:[0,1,1]
	v_pk_fma_f32 v[236:237], v[218:219], v[50:51], v[236:237] op_sel:[1,0,0] op_sel_hi:[1,1,1]
	v_pk_fma_f32 v[238:239], v[38:39], v[42:43], v[236:237] op_sel:[0,0,0] op_sel_hi:[0,1,1]
	v_pk_fma_f32 v[42:43], v[38:39], v[42:43], v[238:239] op_sel:[1,1,0] op_sel_hi:[1,0,1] neg_lo:[1,0,0] neg_hi:[0,0,0]
	v_pk_fma_f32 v[238:239], v[48:49], v[236:237], v[62:63] op_sel:[0,0,0] op_sel_hi:[0,1,1]
	v_pk_fma_f32 v[62:63], v[48:49], v[236:237], v[238:239] op_sel:[1,1,0] op_sel_hi:[1,0,1] neg_lo:[1,0,0] neg_hi:[0,0,0]
	v_pk_mul_f32 v[238:239], v[46:47], v[48:49] op_sel:[0,0] op_sel_hi:[0,1]
	v_pk_fma_f32 v[48:49], v[46:47], v[48:49], v[238:239] op_sel:[1,1,0] op_sel_hi:[1,0,1] neg_lo:[1,0,0] neg_hi:[0,0,0]
	ds_read_b128 v[204:207], v45 offset:128
	ds_read_b128 v[208:211], v45 offset:144
	ds_read_b128 v[212:215], v45 offset:160
	ds_read_b128 v[216:219], v45 offset:176
	s_waitcnt lgkmcnt(4)
	v_pk_mul_f32 v[236:237], v[220:221], v[12:13] op_sel:[0,0] op_sel_hi:[0,1]
	v_pk_fma_f32 v[236:237], v[220:221], v[56:57], v[236:237] op_sel:[1,0,0] op_sel_hi:[1,1,1]
	v_pk_fma_f32 v[236:237], v[222:223], v[14:15], v[236:237] op_sel:[0,0,0] op_sel_hi:[0,1,1]
	v_pk_fma_f32 v[236:237], v[222:223], v[54:55], v[236:237] op_sel:[1,0,0] op_sel_hi:[1,1,1]
	v_pk_fma_f32 v[236:237], v[224:225], v[8:9], v[236:237] op_sel:[0,0,0] op_sel_hi:[0,1,1]
	v_pk_fma_f32 v[236:237], v[224:225], v[52:53], v[236:237] op_sel:[1,0,0] op_sel_hi:[1,1,1]
	v_pk_fma_f32 v[236:237], v[226:227], v[10:11], v[236:237] op_sel:[0,0,0] op_sel_hi:[0,1,1]
	v_pk_fma_f32 v[236:237], v[226:227], v[24:25], v[236:237] op_sel:[1,0,0] op_sel_hi:[1,1,1]
	v_pk_fma_f32 v[236:237], v[228:229], v[4:5], v[236:237] op_sel:[0,0,0] op_sel_hi:[0,1,1]
	v_pk_fma_f32 v[236:237], v[228:229], v[26:27], v[236:237] op_sel:[1,0,0] op_sel_hi:[1,1,1]
	v_pk_fma_f32 v[236:237], v[230:231], v[6:7], v[236:237] op_sel:[0,0,0] op_sel_hi:[0,1,1]
	v_pk_fma_f32 v[236:237], v[230:231], v[28:29], v[236:237] op_sel:[1,0,0] op_sel_hi:[1,1,1]
	v_pk_fma_f32 v[236:237], v[232:233], v[0:1], v[236:237] op_sel:[0,0,0] op_sel_hi:[0,1,1]
	v_pk_fma_f32 v[236:237], v[232:233], v[30:31], v[236:237] op_sel:[1,0,0] op_sel_hi:[1,1,1]
	v_pk_fma_f32 v[236:237], v[234:235], v[2:3], v[236:237] op_sel:[0,0,0] op_sel_hi:[0,1,1]
	v_pk_fma_f32 v[236:237], v[234:235], v[50:51], v[236:237] op_sel:[1,0,0] op_sel_hi:[1,1,1]
	v_pk_fma_f32 v[238:239], v[38:39], v[42:43], v[236:237] op_sel:[0,0,0] op_sel_hi:[0,1,1]
	v_pk_fma_f32 v[42:43], v[38:39], v[42:43], v[238:239] op_sel:[1,1,0] op_sel_hi:[1,0,1] neg_lo:[1,0,0] neg_hi:[0,0,0]
	v_pk_fma_f32 v[238:239], v[48:49], v[236:237], v[62:63] op_sel:[0,0,0] op_sel_hi:[0,1,1]
	v_pk_fma_f32 v[62:63], v[48:49], v[236:237], v[238:239] op_sel:[1,1,0] op_sel_hi:[1,0,1] neg_lo:[1,0,0] neg_hi:[0,0,0]
	v_pk_mul_f32 v[238:239], v[46:47], v[48:49] op_sel:[0,0] op_sel_hi:[0,1]
	v_pk_fma_f32 v[48:49], v[46:47], v[48:49], v[238:239] op_sel:[1,1,0] op_sel_hi:[1,0,1] neg_lo:[1,0,0] neg_hi:[0,0,0]
	ds_read_b128 v[220:223], v45 offset:192
	ds_read_b128 v[224:227], v45 offset:208
	ds_read_b128 v[228:231], v45 offset:224
	ds_read_b128 v[232:235], v45 offset:240
	s_waitcnt lgkmcnt(4)
; DEV void s5_pass1_unit(const Params& p, const Ctx& cx, int l, int unit, char* wl, int lane) {
;     ...
;   for (int t = 0; t < 256; ++t) {
;     h16x8 u0 = *(const h16x8*)(wl + t * 32), u1 = *(const h16x8*)(wl + t * 32 + 16);
;     float br = 0, bi = 0;
; #pragma unroll
;     for (int i = 0; i < 8; ++i) { float u = (float)u0[i]; br = fmaf(u, Br[i], br); bi = fmaf(u, Bi[i], bi); }
; #pragma unroll
;     for (int i = 0; i < 8; ++i) { float u = (float)u1[i]; br = fmaf(u, Br[8 + i], br); bi = fmaf(u, Bi[8 + i], bi); }
;     float nxr = pf.ar * xr - pf.ai * xi + br, nxi = pf.ar * xi + pf.ai * xr + bi;
;     xr = nxr; xi = nxi;
;     yr += pwr * br - pwi * bi; yi += pwr * bi + pwi * br;
;     float npr = pwr * pb.ar - pwi * pb.ai, npi = pwr * pb.ai + pwi * pb.ar;
;     pwr = npr; pwi = npi;
;   }
	v_pk_mul_f32 v[236:237], v[204:205], v[12:13] op_sel:[0,0] op_sel_hi:[0,1]
	v_pk_fma_f32 v[236:237], v[204:205], v[56:57], v[236:237] op_sel:[1,0,0] op_sel_hi:[1,1,1]
	v_pk_fma_f32 v[236:237], v[206:207], v[14:15], v[236:237] op_sel:[0,0,0] op_sel_hi:[0,1,1]
	v_pk_fma_f32 v[236:237], v[206:207], v[54:55], v[236:237] op_sel:[1,0,0] op_sel_hi:[1,1,1]
	v_pk_fma_f32 v[236:237], v[208:209], v[8:9], v[236:237] op_sel:[0,0,0] op_sel_hi:[0,1,1]
	v_pk_fma_f32 v[236:237], v[208:209], v[52:53], v[236:237] op_sel:[1,0,0] op_sel_hi:[1,1,1]
	v_pk_fma_f32 v[236:237], v[210:211], v[10:11], v[236:237] op_sel:[0,0,0] op_sel_hi:[0,1,1]
	v_pk_fma_f32 v[236:237], v[210:211], v[24:25], v[236:237] op_sel:[1,0,0] op_sel_hi:[1,1,1]
	v_pk_fma_f32 v[236:237], v[212:213], v[4:5], v[236:237] op_sel:[0,0,0] op_sel_hi:[0,1,1]
	v_pk_fma_f32 v[236:237], v[212:213], v[26:27], v[236:237] op_sel:[1,0,0] op_sel_hi:[1,1,1]
	v_pk_fma_f32 v[236:237], v[214:215], v[6:7], v[236:237] op_sel:[0,0,0] op_sel_hi:[0,1,1]
	v_pk_fma_f32 v[236:237], v[214:215], v[28:29], v[236:237] op_sel:[1,0,0] op_sel_hi:[1,1,1]
	v_pk_fma_f32 v[236:237], v[216:217], v[0:1], v[236:237] op_sel:[0,0,0] op_sel_hi:[0,1,1]
	v_pk_fma_f32 v[236:237], v[216:217], v[30:31], v[236:237] op_sel:[1,0,0] op_sel_hi:[1,1,1]
	v_pk_fma_f32 v[236:237], v[218:219], v[2:3], v[236:237] op_sel:[0,0,0] op_sel_hi:[0,1,1]
	v_pk_fma_f32 v[236:237], v[218:219], v[50:51], v[236:237] op_sel:[1,0,0] op_sel_hi:[1,1,1]
	v_pk_fma_f32 v[238:239], v[38:39], v[42:43], v[236:237] op_sel:[0,0,0] op_sel_hi:[0,1,1]
	v_pk_fma_f32 v[42:43], v[38:39], v[42:43], v[238:239] op_sel:[1,1,0] op_sel_hi:[1,0,1] neg_lo:[1,0,0] neg_hi:[0,0,0]
	v_pk_fma_f32 v[238:239], v[48:49], v[236:237], v[62:63] op_sel:[0,0,0] op_sel_hi:[0,1,1]
	v_pk_fma_f32 v[62:63], v[48:49], v[236:237], v[238:239] op_sel:[1,1,0] op_sel_hi:[1,0,1] neg_lo:[1,0,0] neg_hi:[0,0,0]
	v_pk_mul_f32 v[238:239], v[46:47], v[48:49] op_sel:[0,0] op_sel_hi:[0,1]
	v_pk_fma_f32 v[48:49], v[46:47], v[48:49], v[238:239] op_sel:[1,1,0] op_sel_hi:[1,0,1] neg_lo:[1,0,0] neg_hi:[0,0,0]
	s_addk_i32 s8, 0x100
	v_add_u32_e32 v45, s8, v33
	ds_read_b128 v[204:207], v45 offset:0
	ds_read_b128 v[208:211], v45 offset:16
	ds_read_b128 v[212:215], v45 offset:32
	ds_read_b128 v[216:219], v45 offset:48
	s_waitcnt lgkmcnt(4)
	v_pk_mul_f32 v[236:237], v[220:221], v[12:13] op_sel:[0,0] op_sel_hi:[0,1]
	v_pk_fma_f32 v[236:237], v[220:221], v[56:57], v[236:237] op_sel:[1,0,0] op_sel_hi:[1,1,1]
	v_pk_fma_f32 v[236:237], v[222:223], v[14:15], v[236:237] op_sel:[0,0,0] op_sel_hi:[0,1,1]
	v_pk_fma_f32 v[236:237], v[222:223], v[54:55], v[236:237] op_sel:[1,0,0] op_sel_hi:[1,1,1]
	v_pk_fma_f32 v[236:237], v[224:225], v[8:9], v[236:237] op_sel:[0,0,0] op_sel_hi:[0,1,1]
	v_pk_fma_f32 v[236:237], v[224:225], v[52:53], v[236:237] op_sel:[1,0,0] op_sel_hi:[1,1,1]
	v_pk_fma_f32 v[236:237], v[226:227], v[10:11], v[236:237] op_sel:[0,0,0] op_sel_hi:[0,1,1]
	v_pk_fma_f32 v[236:237], v[226:227], v[24:25], v[236:237] op_sel:[1,0,0] op_sel_hi:[1,1,1]
	v_pk_fma_f32 v[236:237], v[228:229], v[4:5], v[236:237] op_sel:[0,0,0] op_sel_hi:[0,1,1]
	v_pk_fma_f32 v[236:237], v[228:229], v[26:27], v[236:237] op_sel:[1,0,0] op_sel_hi:[1,1,1]
	v_pk_fma_f32 v[236:237], v[230:231], v[6:7], v[236:237] op_sel:[0,0,0] op_sel_hi:[0,1,1]
	v_pk_fma_f32 v[236:237], v[230:231], v[28:29], v[236:237] op_sel:[1,0,0] op_sel_hi:[1,1,1]
	v_pk_fma_f32 v[236:237], v[232:233], v[0:1], v[236:237] op_sel:[0,0,0] op_sel_hi:[0,1,1]
	v_pk_fma_f32 v[236:237], v[232:233], v[30:31], v[236:237] op_sel:[1,0,0] op_sel_hi:[1,1,1]
	v_pk_fma_f32 v[236:237], v[234:235], v[2:3], v[236:237] op_sel:[0,0,0] op_sel_hi:[0,1,1]
	v_pk_fma_f32 v[236:237], v[234:235], v[50:51], v[236:237] op_sel:[1,0,0] op_sel_hi:[1,1,1]
	v_pk_fma_f32 v[238:239], v[38:39], v[42:43], v[236:237] op_sel:[0,0,0] op_sel_hi:[0,1,1]
	v_pk_fma_f32 v[42:43], v[38:39], v[42:43], v[238:239] op_sel:[1,1,0] op_sel_hi:[1,0,1] neg_lo:[1,0,0] neg_hi:[0,0,0]
	v_pk_fma_f32 v[238:239], v[48:49], v[236:237], v[62:63] op_sel:[0,0,0] op_sel_hi:[0,1,1]
	v_pk_fma_f32 v[62:63], v[48:49], v[236:237], v[238:239] op_sel:[1,1,0] op_sel_hi:[1,0,1] neg_lo:[1,0,0] neg_hi:[0,0,0]
	v_pk_mul_f32 v[238:239], v[46:47], v[48:49] op_sel:[0,0] op_sel_hi:[0,1]
	v_pk_fma_f32 v[48:49], v[46:47], v[48:49], v[238:239] op_sel:[1,1,0] op_sel_hi:[1,0,1] neg_lo:[1,0,0] neg_hi:[0,0,0]
	s_cmpk_lg_i32 s8, 0x4000
	s_cbranch_scc1 .Ls5p1_loop
; DEV S5P s5_params(const Params& p, const Ctx& cx, int l, int d, int g, int lane) {
;     ...
;   float nr = expm1f(xr) * cs - 2.f * sh * sh, ni = e * sn;
;   float inv = 1.f / (lr * lr + li * li);
;   r.br = (nr * lr + ni * li) * inv;
;   r.bi = (ni * lr - nr * li) * inv;
;   return r;
; DEV void s5_pass1_unit(const Params& p, const Ctx& cx, int l, int unit, char* wl, int lane) {
;     ...
;   size_t fi = (((size_t)(b * 32 + g) * 65 + c) * 2) * 64 + lane;
;   F[fi] = make_float2(pf.br * xr - pf.bi * xi, pf.br * xi + pf.bi * xr);
;   F[fi + 64] = make_float2(pb.br * yr - pb.bi * yi, pb.br * yi + pb.bi * yr);
	s_waitcnt lgkmcnt(0)
	v_pk_mul_f32 v[0:1], v[36:37], v[36:37]
	s_mov_b32 s5, 0x43000000
	v_add_f32_e32 v0, v0, v1
	v_div_scale_f32 v1, s[0:1], v0, v0, 1.0
	v_rcp_f32_e32 v2, v1
	v_div_scale_f32 v3, vcc, 1.0, v0, 1.0
	s_mov_b32 s8, 0x42b17217
	v_fma_f32 v4, -v1, v2, 1.0
	v_fmac_f32_e32 v2, v4, v2
	v_mul_f32_e32 v4, v3, v2
	v_fma_f32 v5, -v1, v4, v3
	v_fmac_f32_e32 v4, v5, v2
	v_fma_f32 v1, -v1, v4, v3
	v_div_fmas_f32 v1, v1, v2, v4
	v_div_fixup_f32 v8, v1, v0, 1.0
	v_fmamk_f32 v1, v78, 0xbf317218, v41
	v_fmac_f32_e32 v1, 0x3102e308, v78
	v_fmamk_f32 v2, v1, 0x395133b1, v158
	v_fmaak_f32 v2, v1, v2, 0x3c0887f9
	v_fmaak_f32 v2, v1, v2, 0x3d2aaa81
	v_fmaak_f32 v2, v1, v2, 0x3e2aaaab
	v_ldexp_f32 v0, 1.0, v79
	v_cmp_eq_f32_e32 vcc, s5, v78
	v_fma_f32 v2, v1, v2, 0.5
	v_mul_f32_e32 v2, v1, v2
	v_cndmask_b32_e32 v0, v0, v167, vcc
	v_mul_f32_e32 v3, v74, v74
	v_fmac_f32_e32 v1, v1, v2
	v_add_f32_e32 v2, -1.0, v0
	v_fmamk_f32 v4, v3, 0xb94c1982, v156
	v_fmac_f32_e32 v2, v0, v1
	v_fmaak_f32 v4, v3, v4, 0xbe2aaa9d
	v_add_f32_e32 v0, v2, v2
	v_mul_f32_e32 v4, v3, v4
	v_cndmask_b32_e32 v0, v2, v0, vcc
	v_lshlrev_b32_e32 v2, 30, v76
	v_fmac_f32_e32 v74, v74, v4
	v_fmamk_f32 v4, v3, 0x37d75334, v157
	v_cmp_nlt_f32_e32 vcc, s8, v41
	s_mov_b32 s9, 0xc1880000
	v_xor_b32_e32 v1, v72, v71
	v_and_b32_e32 v2, 0x80000000, v2
	v_fmaak_f32 v4, v3, v4, 0x3d2aabf7
	v_cndmask_b32_e32 v0, v163, v0, vcc
	v_cmp_ngt_f32_e32 vcc, s9, v41
	v_xor_b32_e32 v1, v1, v2
	v_and_b32_e32 v2, 1, v76
	v_fmaak_f32 v4, v3, v4, 0xbf000004
	v_cndmask_b32_e32 v0, -1.0, v0, vcc
	v_fma_f32 v3, v3, v4, 1.0
	v_cmp_eq_u32_e32 vcc, 0, v2
	s_movk_i32 s4, 0x1f8
	v_pk_mul_f32 v[6:7], v[34:35], v[34:35]
	v_cndmask_b32_e32 v2, v3, v74, vcc
	v_xor_b32_e32 v1, v1, v2
	v_cmp_class_f32_e64 vcc, v71, s4
	v_mov_b32_e32 v4, v37
	v_mov_b32_e32 v5, v36
	v_cndmask_b32_e32 v1, v166, v1, vcc
	v_add_f32_e32 v2, v1, v1
	v_mul_f32_e32 v1, v1, v2
	v_fma_f32 v1, v0, v44, -v1
	v_mov_b32_e32 v0, v47
	v_pk_mul_f32 v[2:3], v[36:37], v[0:1]
	v_pk_mul_f32 v[0:1], v[4:5], v[0:1]
	v_sub_f32_e32 v2, v2, v3
	v_add_f32_e32 v3, v6, v7
	v_div_scale_f32 v6, s[0:1], v3, v3, 1.0
	v_rcp_f32_e32 v7, v6
	v_add_f32_e32 v0, v0, v1
	v_mul_f32_e32 v2, v8, v2
	v_mul_f32_e32 v0, v8, v0
	v_fma_f32 v1, -v6, v7, 1.0
	v_fmac_f32_e32 v7, v1, v7
	v_div_scale_f32 v1, vcc, 1.0, v3, 1.0
	v_mul_f32_e32 v4, v1, v7
	v_fma_f32 v5, -v6, v4, v1
	v_fmac_f32_e32 v4, v5, v7
	v_fma_f32 v1, -v6, v4, v1
	v_div_fmas_f32 v1, v1, v7, v4
	v_fmamk_f32 v4, v75, 0xbf317218, v73
	v_fmac_f32_e32 v4, 0x3102e308, v75
	v_fmamk_f32 v5, v4, 0x395133b1, v158
	v_fmaak_f32 v5, v4, v5, 0x3c0887f9
	v_fmaak_f32 v5, v4, v5, 0x3d2aaa81
	v_fmaak_f32 v5, v4, v5, 0x3e2aaaab
	v_div_fixup_f32 v1, v1, v3, 1.0
	v_ldexp_f32 v3, 1.0, v77
	v_cmp_eq_f32_e32 vcc, s5, v75
	v_fma_f32 v5, v4, v5, 0.5
	v_mul_f32_e32 v5, v4, v5
	v_cndmask_b32_e32 v3, v3, v167, vcc
	v_mul_f32_e32 v6, v69, v69
	v_fmac_f32_e32 v4, v4, v5
	v_add_f32_e32 v5, -1.0, v3
	v_fmamk_f32 v7, v6, 0xb94c1982, v156
	v_fmac_f32_e32 v5, v3, v4
	v_fmaak_f32 v7, v6, v7, 0xbe2aaa9d
	v_add_f32_e32 v3, v5, v5
	v_mul_f32_e32 v7, v6, v7
	v_cndmask_b32_e32 v3, v5, v3, vcc
	v_lshlrev_b32_e32 v5, 30, v70
	v_fmac_f32_e32 v69, v69, v7
	v_fmamk_f32 v7, v6, 0x37d75334, v157
	v_cmp_nlt_f32_e32 vcc, s8, v73
	v_xor_b32_e32 v4, v68, v67
	v_and_b32_e32 v5, 0x80000000, v5
	v_fmaak_f32 v7, v6, v7, 0x3d2aabf7
	v_cndmask_b32_e32 v3, v163, v3, vcc
	v_cmp_ngt_f32_e32 vcc, s9, v73
	v_xor_b32_e32 v4, v4, v5
	v_and_b32_e32 v5, 1, v70
	v_fmaak_f32 v7, v6, v7, 0xbf000004
	v_cndmask_b32_e32 v3, -1.0, v3, vcc
	v_fma_f32 v6, v6, v7, 1.0
	v_cmp_eq_u32_e32 vcc, 0, v5
	v_mov_b32_e32 v8, v35
	v_mov_b32_e32 v9, v34
	v_cndmask_b32_e32 v5, v6, v69, vcc
	v_xor_b32_e32 v4, v4, v5
	v_cmp_class_f32_e64 vcc, v67, s4
	v_ashrrev_i32_e32 v33, 31, v32
	s_movk_i32 s0, 0x41
	v_cndmask_b32_e32 v4, v166, v4, vcc
	v_add_f32_e32 v5, v4, v4
	v_mul_f32_e32 v4, v4, v5
	v_fma_f32 v5, v3, v40, -v4
	v_mov_b32_e32 v4, v39
	v_pk_mul_f32 v[6:7], v[34:35], v[4:5]
	v_pk_mul_f32 v[4:5], v[8:9], v[4:5]
	v_sub_f32_e32 v3, v6, v7
	v_mul_f32_e32 v6, v1, v3
	v_add_f32_e32 v3, v4, v5
	v_mad_i64_i32 v[8:9], s[0:1], v65, s0, v[32:33]
	v_mul_f32_e32 v4, v1, v3
	v_readlane_b32 s0, v241, 44
	v_pk_mul_f32 v[6:7], v[6:7], v[42:43] op_sel:[0,1] op_sel_hi:[0,0]
	v_lshlrev_b64 v[8:9], 10, v[8:9]
	v_readlane_b32 s1, v241, 45
	v_pk_fma_f32 v[10:11], v[4:5], v[42:43], v[6:7] neg_lo:[0,0,1] neg_hi:[0,0,1]
	v_pk_fma_f32 v[4:5], v[4:5], v[42:43], v[6:7] op_sel_hi:[0,1,1]
	v_pk_mul_f32 v[2:3], v[2:3], v[62:63] op_sel:[0,1] op_sel_hi:[0,0]
	v_lshl_add_u64 v[8:9], s[0:1], 0, v[8:9]
	v_lshlrev_b32_e32 v128, 3, v66
	v_mov_b32_e32 v11, v5
	v_pk_fma_f32 v[4:5], v[0:1], v[62:63], v[2:3] neg_lo:[0,0,1] neg_hi:[0,0,1]
	v_pk_fma_f32 v[0:1], v[0:1], v[62:63], v[2:3] op_sel_hi:[0,1,1]
	v_lshl_add_u64 v[8:9], v[8:9], 0, v[128:129]
	v_mov_b32_e32 v5, v1
	global_store_dwordx2 v[8:9], v[10:11], off
	global_store_dwordx2 v[8:9], v[4:5], off offset:512
	s_branch .LBB0_305
